# SwiGLU epilogue: H stores as SGPR base + one 32-bit lane offset (per-store 64-bit address VALU -> SALU); store-data WAR pads restored after earlier v_mul removal
# speedup vs baseline: 1.0032x; 1.0032x over previous
; __device__ __forceinline__ unsigned cvt_pk_bf16(float lo, float hi) { unsigned r; asm volatile("v_cvt_pk_bf16_f32 %0, %1, %2" : "=v"(r) : "v"(lo), "v"(hi)); return r; }
; __device__ __forceinline__ float silu_f(float g) { return g * __builtin_amdgcn_rcpf(1.0f + __builtin_amdgcn_exp2f(-1.4426950408889634f * g)); }
;     __device__ __forceinline__ void operator()(const f32x4 (&acc)[2][2][4][2], const Unit& u, int wr, int wc, int fr, int fq) const {
;         const int row0 = u.pm * BM + wr * 64 + fr, col0 = u.pn * 128 + wc * 32 + 8 * fq;
; #pragma unroll
;         for (int ai = 0; ai < 2; ++ai)
; #pragma unroll
;             for (int m = 0; m < 4; ++m) {
;                 bf16_t* rowp = H + (size_t)(row0 + ai * HALF + m * 16) * DFF + col0;
;                 const f32x4 g0 = acc[ai][0][m][0], g1 = acc[ai][0][m][1], u0 = acc[ai][1][m][0], u1 = acc[ai][1][m][1];
;                 u32x4 w;
;                 w.x = cvt_pk_bf16(silu_f(g0[0]) * u0[0], silu_f(g0[1]) * u0[1]); w.y = cvt_pk_bf16(silu_f(g0[2]) * u0[2], silu_f(g0[3]) * u0[3]);
;                 w.z = cvt_pk_bf16(silu_f(g1[0]) * u1[0], silu_f(g1[1]) * u1[1]); w.w = cvt_pk_bf16(silu_f(g1[2]) * u1[2], silu_f(g1[3]) * u1[3]);
;                 *(u32x4*)rowp = w;
;             }
;     }
.LBB0_327:
	v_exp_f32_e64 v154, -v125
	v_lshl_or_b32 v144, s42, 7, v148
	v_lshl_add_u32 v150, s6, 8, v146
	v_add_f32_e32 v154, 1.0, v154
	v_rcp_f32_e32 v154, v154
	v_exp_f32_e64 v151, -v124
	v_mul_lo_u32 v156, v150, s47
	v_lshl_add_u32 v156, v144, 1, v156
	v_mul_f32_e32 v152, v125, v154
	v_exp_f32_e64 v153, -v126
	v_exp_f32_e64 v154, -v127
	v_add_f32_e32 v151, 1.0, v151
	v_rcp_f32_e32 v151, v151
	v_add_f32_e32 v153, 1.0, v153
	v_add_f32_e32 v154, 1.0, v154
	v_rcp_f32_e32 v153, v153
	v_rcp_f32_e32 v154, v154
	v_mul_f32_e32 v151, v124, v151
	v_mul_f32_e32 v151, v151, v92
	v_mul_f32_e32 v152, v152, v93
	v_cvt_pk_bf16_f32 v152, v151, v152
	v_mul_f32_e32 v151, v126, v153
	v_mul_f32_e32 v153, v127, v154
	v_exp_f32_e64 v154, -v120
	v_exp_f32_e64 v155, -v121
	v_mul_f32_e32 v151, v151, v94
	v_mul_f32_e32 v153, v153, v95
	v_add_f32_e32 v154, 1.0, v154
	v_add_f32_e32 v155, 1.0, v155
	v_rcp_f32_e32 v154, v154
	v_rcp_f32_e32 v155, v155
	v_cvt_pk_bf16_f32 v153, v151, v153
	v_mul_f32_e32 v151, v120, v154
	v_mul_f32_e32 v154, v121, v155
	v_exp_f32_e64 v155, -v122
	v_exp_f32_e64 v158, -v123
	v_mul_f32_e32 v151, v151, v88
	v_mul_f32_e32 v154, v154, v89
	v_add_f32_e32 v155, 1.0, v155
	v_add_f32_e32 v158, 1.0, v158
	v_rcp_f32_e32 v155, v155
	v_rcp_f32_e32 v158, v158
	v_cvt_pk_bf16_f32 v154, v151, v154
	s_add_u32 s34, s25, 0xffffff00
	v_mul_f32_e32 v151, v122, v155
	v_mul_f32_e32 v155, v123, v158
	v_mul_f32_e32 v155, v155, v91
	v_mul_f32_e32 v151, v151, v90
	v_cvt_pk_bf16_f32 v155, v151, v155
	global_store_dwordx4 v156, v[152:155], s[16:17]
	s_nop 0
	s_nop 0
	v_exp_f32_e64 v154, -v116
	v_exp_f32_e64 v155, -v117
	v_add_f32_e32 v151, 1.0, v154
	v_add_f32_e32 v154, 1.0, v155
	v_rcp_f32_e32 v154, v154
	v_exp_f32_e64 v153, -v118
	v_mul_f32_e32 v152, v117, v154
	v_exp_f32_e64 v154, -v119
	v_rcp_f32_e32 v151, v151
	v_add_f32_e32 v153, 1.0, v153
	v_rcp_f32_e32 v153, v153
	v_add_f32_e32 v154, 1.0, v154
	v_rcp_f32_e32 v154, v154
	v_mul_f32_e32 v151, v116, v151
	v_mul_f32_e32 v151, v151, v84
	v_mul_f32_e32 v152, v152, v85
	v_cvt_pk_bf16_f32 v152, v151, v152
	v_mul_f32_e32 v151, v118, v153
	v_mul_f32_e32 v153, v119, v154
	v_exp_f32_e64 v154, -v112
	v_exp_f32_e64 v155, -v113
	v_mul_f32_e32 v151, v151, v86
	v_mul_f32_e32 v153, v153, v87
	v_add_f32_e32 v154, 1.0, v154
	v_add_f32_e32 v155, 1.0, v155
	v_rcp_f32_e32 v154, v154
	v_rcp_f32_e32 v155, v155
	v_cvt_pk_bf16_f32 v153, v151, v153
	v_exp_f32_e64 v158, -v115
	v_mul_f32_e32 v151, v112, v154
	v_mul_f32_e32 v154, v113, v155
	v_exp_f32_e64 v155, -v114
	v_add_f32_e32 v158, 1.0, v158
	v_rcp_f32_e32 v158, v158
	v_mul_f32_e32 v151, v151, v80
	v_add_f32_e32 v155, 1.0, v155
	v_rcp_f32_e32 v155, v155
	v_mul_f32_e32 v154, v154, v81
	v_cvt_pk_bf16_f32 v154, v151, v154
	s_addc_u32 s35, s51, -1
	v_mul_f32_e32 v151, v114, v155
	v_mul_f32_e32 v155, v115, v158
	v_mul_f32_e32 v155, v155, v83
	v_mul_f32_e32 v151, v151, v82
	v_cvt_pk_bf16_f32 v155, v151, v155
	s_mul_i32 s98, s47, 16
	s_add_u32 s98, s16, s98
	s_addc_u32 s99, s17, 0
	global_store_dwordx4 v156, v[152:155], s[98:99]
	s_nop 0
	s_nop 0
	v_exp_f32_e64 v154, -v108
	v_exp_f32_e64 v155, -v109
	v_add_f32_e32 v151, 1.0, v154
	v_add_f32_e32 v154, 1.0, v155
	v_rcp_f32_e32 v154, v154
	v_exp_f32_e64 v153, -v110
	v_mul_f32_e32 v152, v109, v154
	v_exp_f32_e64 v154, -v111
	v_rcp_f32_e32 v151, v151
	v_add_f32_e32 v153, 1.0, v153
	v_rcp_f32_e32 v153, v153
	v_add_f32_e32 v154, 1.0, v154
	v_rcp_f32_e32 v154, v154
	v_mul_f32_e32 v151, v108, v151
	v_mul_f32_e32 v151, v151, v76
	v_mul_f32_e32 v152, v152, v77
	v_cvt_pk_bf16_f32 v152, v151, v152
	v_mul_f32_e32 v151, v110, v153
	v_mul_f32_e32 v153, v111, v154
	v_exp_f32_e64 v154, -v104
	v_exp_f32_e64 v155, -v105
	v_mul_f32_e32 v151, v151, v78
	v_mul_f32_e32 v153, v153, v79
	v_add_f32_e32 v154, 1.0, v154
	v_add_f32_e32 v155, 1.0, v155
	v_rcp_f32_e32 v154, v154
	v_rcp_f32_e32 v155, v155
	v_cvt_pk_bf16_f32 v153, v151, v153
	v_exp_f32_e64 v158, -v107
	v_mul_f32_e32 v151, v104, v154
	v_mul_f32_e32 v154, v105, v155
	v_exp_f32_e64 v155, -v106
	v_add_f32_e32 v158, 1.0, v158
	v_rcp_f32_e32 v158, v158
	v_mul_f32_e32 v151, v151, v72
	v_add_f32_e32 v155, 1.0, v155
	v_rcp_f32_e32 v155, v155
	v_mul_f32_e32 v154, v154, v73
	v_cvt_pk_bf16_f32 v154, v151, v154
	s_andn2_b64 vcc, exec, s[36:37]
	v_mul_f32_e32 v151, v106, v155
	v_mul_f32_e32 v155, v107, v158
	v_mul_f32_e32 v155, v155, v75
	v_mul_f32_e32 v151, v151, v74
	v_cvt_pk_bf16_f32 v155, v151, v155
	s_mul_i32 s98, s47, 32
	s_add_u32 s98, s16, s98
	s_addc_u32 s99, s17, 0
	global_store_dwordx4 v156, v[152:155], s[98:99]
	s_nop 0
	s_nop 0
	v_exp_f32_e64 v154, -v100
	v_exp_f32_e64 v155, -v101
	v_add_f32_e32 v151, 1.0, v154
	v_add_f32_e32 v154, 1.0, v155
	v_rcp_f32_e32 v154, v154
	v_exp_f32_e64 v153, -v102
	v_mul_f32_e32 v152, v101, v154
	v_exp_f32_e64 v154, -v103
	v_rcp_f32_e32 v151, v151
	v_add_f32_e32 v153, 1.0, v153
	v_rcp_f32_e32 v153, v153
	v_add_f32_e32 v154, 1.0, v154
	v_rcp_f32_e32 v154, v154
	v_mul_f32_e32 v151, v100, v151
	v_mul_f32_e32 v151, v151, v68
	v_mul_f32_e32 v152, v152, v69
	v_cvt_pk_bf16_f32 v152, v151, v152
	v_mul_f32_e32 v151, v102, v153
	v_mul_f32_e32 v153, v103, v154
	v_exp_f32_e64 v154, -v96
	v_exp_f32_e64 v155, -v97
	v_mul_f32_e32 v151, v151, v70
	v_mul_f32_e32 v153, v153, v71
	v_add_f32_e32 v154, 1.0, v154
	v_add_f32_e32 v155, 1.0, v155
	v_rcp_f32_e32 v154, v154
	v_rcp_f32_e32 v155, v155
	v_cvt_pk_bf16_f32 v153, v151, v153
	v_exp_f32_e64 v158, -v99
	v_mul_f32_e32 v151, v96, v154
	v_mul_f32_e32 v154, v97, v155
	v_exp_f32_e64 v155, -v98
	v_add_f32_e32 v158, 1.0, v158
	v_rcp_f32_e32 v158, v158
	v_mul_f32_e32 v151, v151, v64
	v_add_f32_e32 v155, 1.0, v155
	v_rcp_f32_e32 v155, v155
; __device__ __forceinline__ unsigned cvt_pk_bf16(float lo, float hi) { unsigned r; asm volatile("v_cvt_pk_bf16_f32 %0, %1, %2" : "=v"(r) : "v"(lo), "v"(hi)); return r; }
; __device__ __forceinline__ float silu_f(float g) { return g * __builtin_amdgcn_rcpf(1.0f + __builtin_amdgcn_exp2f(-1.4426950408889634f * g)); }
; #define PG8_BAR __builtin_amdgcn_s_barrier()
; template <class Epi, bool BSEL = false>
; __device__ __forceinline__ void gemm_phase(LAS unsigned char* lds, const Gemm g, const Order& S, const Epi& E, const int tid) {
;     ...
;         if (!has_next) break;
; #pragma unroll
;         for (int a = 0; a < 2; ++a)
; #pragma unroll
;             for (int b = 0; b < 2; ++b)
; #pragma unroll
;                 for (int m = 0; m < 4; ++m)
; #pragma unroll
;                     for (int n = 0; n < 2; ++n) acc[a][b][m][n] = (f32x4){0.f, 0.f, 0.f, 0.f};
;         cur = nxt; cA = nA; cB = nB; cP = nP; chB = nhB; ++ui;
;         if constexpr (ALIGN_EPI) { if (wr == 1) PG8_BAR; }
;     __device__ __forceinline__ void operator()(const f32x4 (&acc)[2][2][4][2], const Unit& u, int wr, int wc, int fr, int fq) const {
;         const int row0 = u.pm * BM + wr * 64 + fr, col0 = u.pn * 128 + wc * 32 + 8 * fq;
; #pragma unroll
;         for (int ai = 0; ai < 2; ++ai)
; #pragma unroll
;             for (int m = 0; m < 4; ++m) {
;                 bf16_t* rowp = H + (size_t)(row0 + ai * HALF + m * 16) * DFF + col0;
;                 const f32x4 g0 = acc[ai][0][m][0], g1 = acc[ai][0][m][1], u0 = acc[ai][1][m][0], u1 = acc[ai][1][m][1];
;                 u32x4 w;
;                 w.x = cvt_pk_bf16(silu_f(g0[0]) * u0[0], silu_f(g0[1]) * u0[1]); w.y = cvt_pk_bf16(silu_f(g0[2]) * u0[2], silu_f(g0[3]) * u0[3]);
;                 w.z = cvt_pk_bf16(silu_f(g1[0]) * u1[0], silu_f(g1[1]) * u1[1]); w.w = cvt_pk_bf16(silu_f(g1[2]) * u1[2], silu_f(g1[3]) * u1[3]);
;                 *(u32x4*)rowp = w;
;             }
;     }
	v_mul_f32_e32 v154, v154, v65
	v_cvt_pk_bf16_f32 v154, v151, v154
	v_mul_f32_e32 v151, v98, v155
	v_mul_f32_e32 v155, v99, v158
	v_mul_f32_e32 v155, v155, v67
	v_mul_f32_e32 v151, v151, v66
	v_cvt_pk_bf16_f32 v155, v151, v155
	s_mul_i32 s98, s47, 48
	s_add_u32 s98, s16, s98
	s_addc_u32 s99, s17, 0
	global_store_dwordx4 v156, v[152:155], s[98:99]
	s_nop 0
	s_nop 0
	v_exp_f32_e64 v154, -v60
	v_exp_f32_e64 v155, -v61
	v_add_f32_e32 v151, 1.0, v154
	v_add_f32_e32 v154, 1.0, v155
	v_rcp_f32_e32 v154, v154
	v_exp_f32_e64 v153, -v62
	v_mul_f32_e32 v152, v61, v154
	v_exp_f32_e64 v154, -v63
	v_rcp_f32_e32 v151, v151
	v_add_f32_e32 v153, 1.0, v153
	v_rcp_f32_e32 v153, v153
	v_add_f32_e32 v154, 1.0, v154
	v_rcp_f32_e32 v154, v154
	v_mul_f32_e32 v151, v60, v151
	v_mul_f32_e32 v151, v151, v28
	v_mul_f32_e32 v152, v152, v29
	v_cvt_pk_bf16_f32 v152, v151, v152
	v_mul_f32_e32 v151, v62, v153
	v_mul_f32_e32 v153, v63, v154
	v_exp_f32_e64 v154, -v56
	v_exp_f32_e64 v155, -v57
	v_mul_f32_e32 v151, v151, v30
	v_mul_f32_e32 v153, v153, v31
	v_add_f32_e32 v154, 1.0, v154
	v_add_f32_e32 v155, 1.0, v155
	v_rcp_f32_e32 v154, v154
	v_rcp_f32_e32 v155, v155
	v_cvt_pk_bf16_f32 v153, v151, v153
	v_exp_f32_e64 v158, -v59
	v_mul_f32_e32 v151, v56, v154
	v_mul_f32_e32 v154, v57, v155
	v_exp_f32_e64 v155, -v58
	v_add_f32_e32 v158, 1.0, v158
	v_rcp_f32_e32 v158, v158
	v_mul_f32_e32 v151, v151, v24
	v_add_f32_e32 v155, 1.0, v155
	v_rcp_f32_e32 v155, v155
	v_mul_f32_e32 v154, v154, v25
	v_cvt_pk_bf16_f32 v154, v151, v154
	v_mul_f32_e32 v151, v58, v155
	v_mul_f32_e32 v155, v59, v158
	v_mul_f32_e32 v155, v155, v27
	v_mul_f32_e32 v151, v151, v26
	v_cvt_pk_bf16_f32 v155, v151, v155
	s_mul_i32 s98, s47, 128
	s_add_u32 s98, s16, s98
	s_addc_u32 s99, s17, 0
	global_store_dwordx4 v156, v[152:155], s[98:99]
	s_nop 0
	s_nop 0
	v_exp_f32_e64 v154, -v52
	v_exp_f32_e64 v155, -v53
	v_add_f32_e32 v151, 1.0, v154
	v_add_f32_e32 v154, 1.0, v155
	v_rcp_f32_e32 v154, v154
	v_exp_f32_e64 v153, -v54
	v_mul_f32_e32 v152, v53, v154
	v_exp_f32_e64 v154, -v55
	v_rcp_f32_e32 v151, v151
	v_add_f32_e32 v153, 1.0, v153
	v_rcp_f32_e32 v153, v153
	v_add_f32_e32 v154, 1.0, v154
	v_rcp_f32_e32 v154, v154
	v_mul_f32_e32 v151, v52, v151
	v_mul_f32_e32 v151, v151, v20
	v_mul_f32_e32 v152, v152, v21
	v_cvt_pk_bf16_f32 v152, v151, v152
	v_mul_f32_e32 v151, v54, v153
	v_mul_f32_e32 v153, v55, v154
	v_exp_f32_e64 v154, -v48
	v_exp_f32_e64 v155, -v49
	v_mul_f32_e32 v151, v151, v22
	v_mul_f32_e32 v153, v153, v23
	v_add_f32_e32 v154, 1.0, v154
	v_add_f32_e32 v155, 1.0, v155
	v_rcp_f32_e32 v154, v154
	v_rcp_f32_e32 v155, v155
	v_cvt_pk_bf16_f32 v153, v151, v153
	v_exp_f32_e64 v158, -v51
	v_mul_f32_e32 v151, v48, v154
	v_mul_f32_e32 v154, v49, v155
	v_exp_f32_e64 v155, -v50
	v_add_f32_e32 v158, 1.0, v158
	v_rcp_f32_e32 v158, v158
	v_mul_f32_e32 v151, v151, v16
	v_add_f32_e32 v155, 1.0, v155
	v_rcp_f32_e32 v155, v155
	v_mul_f32_e32 v154, v154, v17
	v_cvt_pk_bf16_f32 v154, v151, v154
	v_mul_f32_e32 v151, v50, v155
	v_mul_f32_e32 v155, v51, v158
	v_mul_f32_e32 v155, v155, v19
	v_mul_f32_e32 v151, v151, v18
	v_cvt_pk_bf16_f32 v155, v151, v155
	s_mul_i32 s98, s47, 144
	s_add_u32 s98, s16, s98
	s_addc_u32 s99, s17, 0
	global_store_dwordx4 v156, v[152:155], s[98:99]
	s_nop 0
	s_nop 0
	v_exp_f32_e64 v154, -v44
	v_exp_f32_e64 v155, -v45
	v_add_f32_e32 v151, 1.0, v154
	v_add_f32_e32 v154, 1.0, v155
	v_rcp_f32_e32 v154, v154
	v_exp_f32_e64 v153, -v46
	v_mul_f32_e32 v152, v45, v154
	v_exp_f32_e64 v154, -v47
	v_rcp_f32_e32 v151, v151
	v_add_f32_e32 v153, 1.0, v153
	v_rcp_f32_e32 v153, v153
	v_add_f32_e32 v154, 1.0, v154
	v_rcp_f32_e32 v154, v154
	v_mul_f32_e32 v151, v44, v151
	v_mul_f32_e32 v151, v151, v12
	v_mul_f32_e32 v152, v152, v13
	v_cvt_pk_bf16_f32 v152, v151, v152
	v_mul_f32_e32 v151, v46, v153
	v_mul_f32_e32 v153, v47, v154
	v_exp_f32_e64 v154, -v40
	v_exp_f32_e64 v155, -v41
	v_mul_f32_e32 v151, v151, v14
	v_mul_f32_e32 v153, v153, v15
	v_add_f32_e32 v154, 1.0, v154
	v_add_f32_e32 v155, 1.0, v155
	v_rcp_f32_e32 v154, v154
	v_rcp_f32_e32 v155, v155
	v_cvt_pk_bf16_f32 v153, v151, v153
	v_exp_f32_e64 v158, -v43
	v_mul_f32_e32 v151, v40, v154
	v_mul_f32_e32 v154, v41, v155
	v_exp_f32_e64 v155, -v42
	v_add_f32_e32 v158, 1.0, v158
	v_rcp_f32_e32 v158, v158
	v_mul_f32_e32 v151, v151, v8
	v_add_f32_e32 v155, 1.0, v155
	v_rcp_f32_e32 v155, v155
	v_mul_f32_e32 v154, v154, v9
	v_cvt_pk_bf16_f32 v154, v151, v154
	v_mul_f32_e32 v151, v42, v155
	v_mul_f32_e32 v155, v43, v158
	v_mul_f32_e32 v151, v151, v10
	v_mul_f32_e32 v155, v155, v11
	v_cvt_pk_bf16_f32 v155, v151, v155
	s_mul_i32 s98, s47, 160
	s_add_u32 s98, s16, s98
	s_addc_u32 s99, s17, 0
	global_store_dwordx4 v156, v[152:155], s[98:99]
	s_nop 0
	v_exp_f32_e64 v151, -v36
	v_exp_f32_e64 v152, -v37
	v_add_f32_e32 v150, 1.0, v151
	v_rcp_f32_e32 v153, v150
	v_add_f32_e32 v150, 1.0, v152
	v_rcp_f32_e32 v152, v150
	v_exp_f32_e64 v144, -v38
	v_exp_f32_e64 v145, -v39
	v_mul_f32_e32 v142, v36, v153
	v_mul_f32_e32 v143, v37, v152
	v_add_f32_e32 v144, 1.0, v144
	v_add_f32_e32 v145, 1.0, v145
	v_rcp_f32_e32 v144, v144
	v_rcp_f32_e32 v145, v145
	v_mul_f32_e32 v142, v142, v4
	v_mul_f32_e32 v143, v143, v5
	v_cvt_pk_bf16_f32 v142, v142, v143
	v_mul_f32_e32 v143, v38, v144
	v_mul_f32_e32 v144, v39, v145
	v_exp_f32_e64 v145, -v32
	v_exp_f32_e64 v152, -v33
	v_mul_f32_e32 v143, v143, v6
	v_mul_f32_e32 v144, v144, v7
	v_add_f32_e32 v145, 1.0, v145
	v_add_f32_e32 v152, 1.0, v152
	v_rcp_f32_e32 v145, v145
	v_rcp_f32_e32 v152, v152
	v_cvt_pk_bf16_f32 v143, v143, v144
	v_mul_f32_e32 v144, v32, v145
	v_mul_f32_e32 v145, v33, v152
	v_exp_f32_e64 v152, -v34
	v_exp_f32_e64 v153, -v35
	v_mul_f32_e32 v144, v144, v0
	v_mul_f32_e32 v145, v145, v1
	v_add_f32_e32 v152, 1.0, v152
	v_rcp_f32_e32 v152, v152
	v_add_f32_e32 v153, 1.0, v153
	v_rcp_f32_e32 v153, v153
	v_cvt_pk_bf16_f32 v144, v144, v145
	v_mul_f32_e32 v145, v34, v152
	v_mul_f32_e32 v145, v145, v2
	v_mul_f32_e32 v152, v35, v153
	v_mul_f32_e32 v152, v152, v3
	v_cvt_pk_bf16_f32 v145, v145, v152
	s_mul_i32 s98, s47, 176
	s_add_u32 s98, s16, s98
	s_addc_u32 s99, s17, 0
	global_store_dwordx4 v156, v[142:145], s[98:99]
	s_cbranch_vccnz .LBB0_318
	s_andn2_b64 vcc, exec, s[10:11]
	s_cbranch_vccnz .LBB0_317
	s_barrier
	s_branch .LBB0_317

; __device__ __forceinline__ unsigned cvt_pk_bf16(float lo, float hi) { unsigned r; asm volatile("v_cvt_pk_bf16_f32 %0, %1, %2" : "=v"(r) : "v"(lo), "v"(hi)); return r; }
; __device__ __forceinline__ float silu_f(float g) { return g * __builtin_amdgcn_rcpf(1.0f + __builtin_amdgcn_exp2f(-1.4426950408889634f * g)); }
;     __device__ __forceinline__ void operator()(const f32x4 (&acc)[2][2][4][2], const Unit& u, int wr, int wc, int fr, int fq) const {
;         const int row0 = u.pm * BM + wr * 64 + fr, col0 = u.pn * 128 + wc * 32 + 8 * fq;
; #pragma unroll
;         for (int ai = 0; ai < 2; ++ai)
; #pragma unroll
;             for (int m = 0; m < 4; ++m) {
;                 bf16_t* rowp = H + (size_t)(row0 + ai * HALF + m * 16) * DFF + col0;
;                 const f32x4 g0 = acc[ai][0][m][0], g1 = acc[ai][0][m][1], u0 = acc[ai][1][m][0], u1 = acc[ai][1][m][1];
;                 u32x4 w;
;                 w.x = cvt_pk_bf16(silu_f(g0[0]) * u0[0], silu_f(g0[1]) * u0[1]); w.y = cvt_pk_bf16(silu_f(g0[2]) * u0[2], silu_f(g0[3]) * u0[3]);
;                 w.z = cvt_pk_bf16(silu_f(g1[0]) * u1[0], silu_f(g1[1]) * u1[1]); w.w = cvt_pk_bf16(silu_f(g1[2]) * u1[2], silu_f(g1[3]) * u1[3]);
;                 *(u32x4*)rowp = w;
;             }
;     }
.LBB0_1274:
	v_exp_f32_e64 v154, -v125
	v_lshl_or_b32 v144, s42, 7, v148
	v_lshl_add_u32 v150, s6, 8, v146
	v_add_f32_e32 v154, 1.0, v154
	v_rcp_f32_e32 v154, v154
	v_exp_f32_e64 v151, -v124
	v_mul_lo_u32 v156, v150, s47
	v_lshl_add_u32 v156, v144, 1, v156
	v_mul_f32_e32 v152, v125, v154
	v_exp_f32_e64 v153, -v126
	v_exp_f32_e64 v154, -v127
	v_add_f32_e32 v151, 1.0, v151
	v_rcp_f32_e32 v151, v151
	v_add_f32_e32 v153, 1.0, v153
	v_add_f32_e32 v154, 1.0, v154
	v_rcp_f32_e32 v153, v153
	v_rcp_f32_e32 v154, v154
	v_mul_f32_e32 v151, v124, v151
	v_mul_f32_e32 v151, v151, v92
	v_mul_f32_e32 v152, v152, v93
	v_cvt_pk_bf16_f32 v152, v151, v152
	v_mul_f32_e32 v151, v126, v153
	v_mul_f32_e32 v153, v127, v154
	v_exp_f32_e64 v154, -v120
	v_exp_f32_e64 v155, -v121
	v_mul_f32_e32 v151, v151, v94
	v_mul_f32_e32 v153, v153, v95
	v_add_f32_e32 v154, 1.0, v154
	v_add_f32_e32 v155, 1.0, v155
	v_rcp_f32_e32 v154, v154
	v_rcp_f32_e32 v155, v155
	v_cvt_pk_bf16_f32 v153, v151, v153
	v_mul_f32_e32 v151, v120, v154
	v_mul_f32_e32 v154, v121, v155
	v_exp_f32_e64 v155, -v122
	v_exp_f32_e64 v158, -v123
	v_mul_f32_e32 v151, v151, v88
	v_mul_f32_e32 v154, v154, v89
	v_add_f32_e32 v155, 1.0, v155
	v_add_f32_e32 v158, 1.0, v158
	v_rcp_f32_e32 v155, v155
	v_rcp_f32_e32 v158, v158
	v_cvt_pk_bf16_f32 v154, v151, v154
	s_add_u32 s36, s27, 0xffffff00
	v_mul_f32_e32 v151, v122, v155
	v_mul_f32_e32 v155, v123, v158
	v_mul_f32_e32 v155, v155, v91
	v_mul_f32_e32 v151, v151, v90
	v_cvt_pk_bf16_f32 v155, v151, v155
	global_store_dwordx4 v156, v[152:155], s[16:17]
	s_nop 0
	s_nop 0
	v_exp_f32_e64 v154, -v116
	v_exp_f32_e64 v155, -v117
	v_add_f32_e32 v151, 1.0, v154
	v_add_f32_e32 v154, 1.0, v155
	v_rcp_f32_e32 v154, v154
	v_exp_f32_e64 v153, -v118
	v_mul_f32_e32 v152, v117, v154
	v_exp_f32_e64 v154, -v119
	v_rcp_f32_e32 v151, v151
	v_add_f32_e32 v153, 1.0, v153
	v_rcp_f32_e32 v153, v153
	v_add_f32_e32 v154, 1.0, v154
	v_rcp_f32_e32 v154, v154
	v_mul_f32_e32 v151, v116, v151
	v_mul_f32_e32 v151, v151, v84
	v_mul_f32_e32 v152, v152, v85
	v_cvt_pk_bf16_f32 v152, v151, v152
	v_mul_f32_e32 v151, v118, v153
	v_mul_f32_e32 v153, v119, v154
	v_exp_f32_e64 v154, -v112
	v_exp_f32_e64 v155, -v113
	v_mul_f32_e32 v151, v151, v86
	v_mul_f32_e32 v153, v153, v87
	v_add_f32_e32 v154, 1.0, v154
	v_add_f32_e32 v155, 1.0, v155
	v_rcp_f32_e32 v154, v154
	v_rcp_f32_e32 v155, v155
	v_cvt_pk_bf16_f32 v153, v151, v153
	v_exp_f32_e64 v158, -v115
	v_mul_f32_e32 v151, v112, v154
	v_mul_f32_e32 v154, v113, v155
	v_exp_f32_e64 v155, -v114
	v_add_f32_e32 v158, 1.0, v158
	v_rcp_f32_e32 v158, v158
	v_mul_f32_e32 v151, v151, v80
	v_add_f32_e32 v155, 1.0, v155
	v_rcp_f32_e32 v155, v155
	v_mul_f32_e32 v154, v154, v81
	v_cvt_pk_bf16_f32 v154, v151, v154
	s_addc_u32 s37, s51, -1
	v_mul_f32_e32 v151, v114, v155
	v_mul_f32_e32 v155, v115, v158
	v_mul_f32_e32 v155, v155, v83
	v_mul_f32_e32 v151, v151, v82
	v_cvt_pk_bf16_f32 v155, v151, v155
	s_mul_i32 s98, s47, 16
	s_add_u32 s98, s16, s98
	s_addc_u32 s99, s17, 0
	global_store_dwordx4 v156, v[152:155], s[98:99]
	s_nop 0
	s_nop 0
	v_exp_f32_e64 v154, -v108
	v_exp_f32_e64 v155, -v109
	v_add_f32_e32 v151, 1.0, v154
	v_add_f32_e32 v154, 1.0, v155
	v_rcp_f32_e32 v154, v154
	v_exp_f32_e64 v153, -v110
	v_mul_f32_e32 v152, v109, v154
	v_exp_f32_e64 v154, -v111
	v_rcp_f32_e32 v151, v151
	v_add_f32_e32 v153, 1.0, v153
	v_rcp_f32_e32 v153, v153
	v_add_f32_e32 v154, 1.0, v154
	v_rcp_f32_e32 v154, v154
	v_mul_f32_e32 v151, v108, v151
	v_mul_f32_e32 v151, v151, v76
	v_mul_f32_e32 v152, v152, v77
	v_cvt_pk_bf16_f32 v152, v151, v152
	v_mul_f32_e32 v151, v110, v153
	v_mul_f32_e32 v153, v111, v154
	v_exp_f32_e64 v154, -v104
	v_exp_f32_e64 v155, -v105
	v_mul_f32_e32 v151, v151, v78
	v_mul_f32_e32 v153, v153, v79
	v_add_f32_e32 v154, 1.0, v154
	v_add_f32_e32 v155, 1.0, v155
	v_rcp_f32_e32 v154, v154
	v_rcp_f32_e32 v155, v155
	v_cvt_pk_bf16_f32 v153, v151, v153
	v_exp_f32_e64 v158, -v107
	v_mul_f32_e32 v151, v104, v154
	v_mul_f32_e32 v154, v105, v155
	v_exp_f32_e64 v155, -v106
	v_add_f32_e32 v158, 1.0, v158
	v_rcp_f32_e32 v158, v158
	v_mul_f32_e32 v151, v151, v72
	v_add_f32_e32 v155, 1.0, v155
	v_rcp_f32_e32 v155, v155
	v_mul_f32_e32 v154, v154, v73
	v_cvt_pk_bf16_f32 v154, v151, v154
	s_andn2_b64 vcc, exec, s[38:39]
	v_mul_f32_e32 v151, v106, v155
	v_mul_f32_e32 v155, v107, v158
	v_mul_f32_e32 v155, v155, v75
	v_mul_f32_e32 v151, v151, v74
	v_cvt_pk_bf16_f32 v155, v151, v155
	s_mul_i32 s98, s47, 32
	s_add_u32 s98, s16, s98
	s_addc_u32 s99, s17, 0
	global_store_dwordx4 v156, v[152:155], s[98:99]
	s_nop 0
	s_nop 0
	v_exp_f32_e64 v154, -v100
	v_exp_f32_e64 v155, -v101
	v_add_f32_e32 v151, 1.0, v154
	v_add_f32_e32 v154, 1.0, v155
	v_rcp_f32_e32 v154, v154
	v_exp_f32_e64 v153, -v102
	v_mul_f32_e32 v152, v101, v154
	v_exp_f32_e64 v154, -v103
	v_rcp_f32_e32 v151, v151
	v_add_f32_e32 v153, 1.0, v153
	v_rcp_f32_e32 v153, v153
	v_add_f32_e32 v154, 1.0, v154
	v_rcp_f32_e32 v154, v154
	v_mul_f32_e32 v151, v100, v151
	v_mul_f32_e32 v151, v151, v68
	v_mul_f32_e32 v152, v152, v69
	v_cvt_pk_bf16_f32 v152, v151, v152
	v_mul_f32_e32 v151, v102, v153
	v_mul_f32_e32 v153, v103, v154
	v_exp_f32_e64 v154, -v96
	v_exp_f32_e64 v155, -v97
	v_mul_f32_e32 v151, v151, v70
	v_mul_f32_e32 v153, v153, v71
	v_add_f32_e32 v154, 1.0, v154
	v_add_f32_e32 v155, 1.0, v155
	v_rcp_f32_e32 v154, v154
	v_rcp_f32_e32 v155, v155
	v_cvt_pk_bf16_f32 v153, v151, v153
	v_exp_f32_e64 v158, -v99
	v_mul_f32_e32 v151, v96, v154
	v_mul_f32_e32 v154, v97, v155
	v_exp_f32_e64 v155, -v98
	v_add_f32_e32 v158, 1.0, v158
	v_rcp_f32_e32 v158, v158
	v_mul_f32_e32 v151, v151, v64
	v_add_f32_e32 v155, 1.0, v155
	v_rcp_f32_e32 v155, v155
; __device__ __forceinline__ unsigned cvt_pk_bf16(float lo, float hi) { unsigned r; asm volatile("v_cvt_pk_bf16_f32 %0, %1, %2" : "=v"(r) : "v"(lo), "v"(hi)); return r; }
; __device__ __forceinline__ float silu_f(float g) { return g * __builtin_amdgcn_rcpf(1.0f + __builtin_amdgcn_exp2f(-1.4426950408889634f * g)); }
; #define PG8_BAR __builtin_amdgcn_s_barrier()
; template <class Epi, bool BSEL = false>
; __device__ __forceinline__ void gemm_phase(LAS unsigned char* lds, const Gemm g, const Order& S, const Epi& E, const int tid) {
;     ...
;         if constexpr (ALIGN_EPI) { if (wr == 0) PG8_BAR; }
;         if constexpr (!Epi::AFTER_DRAIN) E(acc, cur, wr, wc, fr, fq);
;         if (!has_next) break;
; #pragma unroll
;         for (int a = 0; a < 2; ++a)
; #pragma unroll
;             for (int b = 0; b < 2; ++b)
; #pragma unroll
;                 for (int m = 0; m < 4; ++m)
; #pragma unroll
;                     for (int n = 0; n < 2; ++n) acc[a][b][m][n] = (f32x4){0.f, 0.f, 0.f, 0.f};
;         cur = nxt; cA = nA; cB = nB; cP = nP; chB = nhB; ++ui;
;         if constexpr (ALIGN_EPI) { if (wr == 1) PG8_BAR; }
;     __device__ __forceinline__ void operator()(const f32x4 (&acc)[2][2][4][2], const Unit& u, int wr, int wc, int fr, int fq) const {
;         const int row0 = u.pm * BM + wr * 64 + fr, col0 = u.pn * 128 + wc * 32 + 8 * fq;
; #pragma unroll
;         for (int ai = 0; ai < 2; ++ai)
; #pragma unroll
;             for (int m = 0; m < 4; ++m) {
;                 bf16_t* rowp = H + (size_t)(row0 + ai * HALF + m * 16) * DFF + col0;
;                 const f32x4 g0 = acc[ai][0][m][0], g1 = acc[ai][0][m][1], u0 = acc[ai][1][m][0], u1 = acc[ai][1][m][1];
;                 u32x4 w;
;                 w.x = cvt_pk_bf16(silu_f(g0[0]) * u0[0], silu_f(g0[1]) * u0[1]); w.y = cvt_pk_bf16(silu_f(g0[2]) * u0[2], silu_f(g0[3]) * u0[3]);
;                 w.z = cvt_pk_bf16(silu_f(g1[0]) * u1[0], silu_f(g1[1]) * u1[1]); w.w = cvt_pk_bf16(silu_f(g1[2]) * u1[2], silu_f(g1[3]) * u1[3]);
;                 *(u32x4*)rowp = w;
	v_mul_f32_e32 v154, v154, v65
	v_cvt_pk_bf16_f32 v154, v151, v154
	v_mul_f32_e32 v151, v98, v155
	v_mul_f32_e32 v155, v99, v158
	v_mul_f32_e32 v155, v155, v67
	v_mul_f32_e32 v151, v151, v66
	v_cvt_pk_bf16_f32 v155, v151, v155
	s_mul_i32 s98, s47, 48
	s_add_u32 s98, s16, s98
	s_addc_u32 s99, s17, 0
	global_store_dwordx4 v156, v[152:155], s[98:99]
	s_nop 0
	s_nop 0
	v_exp_f32_e64 v154, -v60
	v_exp_f32_e64 v155, -v61
	v_add_f32_e32 v151, 1.0, v154
	v_add_f32_e32 v154, 1.0, v155
	v_rcp_f32_e32 v154, v154
	v_exp_f32_e64 v153, -v62
	v_mul_f32_e32 v152, v61, v154
	v_exp_f32_e64 v154, -v63
	v_rcp_f32_e32 v151, v151
	v_add_f32_e32 v153, 1.0, v153
	v_rcp_f32_e32 v153, v153
	v_add_f32_e32 v154, 1.0, v154
	v_rcp_f32_e32 v154, v154
	v_mul_f32_e32 v151, v60, v151
	v_mul_f32_e32 v151, v151, v28
	v_mul_f32_e32 v152, v152, v29
	v_cvt_pk_bf16_f32 v152, v151, v152
	v_mul_f32_e32 v151, v62, v153
	v_mul_f32_e32 v153, v63, v154
	v_exp_f32_e64 v154, -v56
	v_exp_f32_e64 v155, -v57
	v_mul_f32_e32 v151, v151, v30
	v_mul_f32_e32 v153, v153, v31
	v_add_f32_e32 v154, 1.0, v154
	v_add_f32_e32 v155, 1.0, v155
	v_rcp_f32_e32 v154, v154
	v_rcp_f32_e32 v155, v155
	v_cvt_pk_bf16_f32 v153, v151, v153
	v_exp_f32_e64 v158, -v59
	v_mul_f32_e32 v151, v56, v154
	v_mul_f32_e32 v154, v57, v155
	v_exp_f32_e64 v155, -v58
	v_add_f32_e32 v158, 1.0, v158
	v_rcp_f32_e32 v158, v158
	v_mul_f32_e32 v151, v151, v24
	v_add_f32_e32 v155, 1.0, v155
	v_rcp_f32_e32 v155, v155
	v_mul_f32_e32 v154, v154, v25
	v_cvt_pk_bf16_f32 v154, v151, v154
	v_mul_f32_e32 v151, v58, v155
	v_mul_f32_e32 v155, v59, v158
	v_mul_f32_e32 v155, v155, v27
	v_mul_f32_e32 v151, v151, v26
	v_cvt_pk_bf16_f32 v155, v151, v155
	s_mul_i32 s98, s47, 128
	s_add_u32 s98, s16, s98
	s_addc_u32 s99, s17, 0
	global_store_dwordx4 v156, v[152:155], s[98:99]
	s_nop 0
	s_nop 0
	v_exp_f32_e64 v154, -v52
	v_exp_f32_e64 v155, -v53
	v_add_f32_e32 v151, 1.0, v154
	v_add_f32_e32 v154, 1.0, v155
	v_rcp_f32_e32 v154, v154
	v_exp_f32_e64 v153, -v54
	v_mul_f32_e32 v152, v53, v154
	v_exp_f32_e64 v154, -v55
	v_rcp_f32_e32 v151, v151
	v_add_f32_e32 v153, 1.0, v153
	v_rcp_f32_e32 v153, v153
	v_add_f32_e32 v154, 1.0, v154
	v_rcp_f32_e32 v154, v154
	v_mul_f32_e32 v151, v52, v151
	v_mul_f32_e32 v151, v151, v20
	v_mul_f32_e32 v152, v152, v21
	v_cvt_pk_bf16_f32 v152, v151, v152
	v_mul_f32_e32 v151, v54, v153
	v_mul_f32_e32 v153, v55, v154
	v_exp_f32_e64 v154, -v48
	v_exp_f32_e64 v155, -v49
	v_mul_f32_e32 v151, v151, v22
	v_mul_f32_e32 v153, v153, v23
	v_add_f32_e32 v154, 1.0, v154
	v_add_f32_e32 v155, 1.0, v155
	v_rcp_f32_e32 v154, v154
	v_rcp_f32_e32 v155, v155
	v_cvt_pk_bf16_f32 v153, v151, v153
	v_exp_f32_e64 v158, -v51
	v_mul_f32_e32 v151, v48, v154
	v_mul_f32_e32 v154, v49, v155
	v_exp_f32_e64 v155, -v50
	v_add_f32_e32 v158, 1.0, v158
	v_rcp_f32_e32 v158, v158
	v_mul_f32_e32 v151, v151, v16
	v_add_f32_e32 v155, 1.0, v155
	v_rcp_f32_e32 v155, v155
	v_mul_f32_e32 v154, v154, v17
	v_cvt_pk_bf16_f32 v154, v151, v154
	v_mul_f32_e32 v151, v50, v155
	v_mul_f32_e32 v155, v51, v158
	v_mul_f32_e32 v155, v155, v19
	v_mul_f32_e32 v151, v151, v18
	v_cvt_pk_bf16_f32 v155, v151, v155
	s_mul_i32 s98, s47, 144
	s_add_u32 s98, s16, s98
	s_addc_u32 s99, s17, 0
	global_store_dwordx4 v156, v[152:155], s[98:99]
	s_nop 0
	s_nop 0
	v_exp_f32_e64 v154, -v44
	v_exp_f32_e64 v155, -v45
	v_add_f32_e32 v151, 1.0, v154
	v_add_f32_e32 v154, 1.0, v155
	v_rcp_f32_e32 v154, v154
	v_exp_f32_e64 v153, -v46
	v_mul_f32_e32 v152, v45, v154
	v_exp_f32_e64 v154, -v47
	v_rcp_f32_e32 v151, v151
	v_add_f32_e32 v153, 1.0, v153
	v_rcp_f32_e32 v153, v153
	v_add_f32_e32 v154, 1.0, v154
	v_rcp_f32_e32 v154, v154
	v_mul_f32_e32 v151, v44, v151
	v_mul_f32_e32 v151, v151, v12
	v_mul_f32_e32 v152, v152, v13
	v_cvt_pk_bf16_f32 v152, v151, v152
	v_mul_f32_e32 v151, v46, v153
	v_mul_f32_e32 v153, v47, v154
	v_exp_f32_e64 v154, -v40
	v_exp_f32_e64 v155, -v41
	v_mul_f32_e32 v151, v151, v14
	v_mul_f32_e32 v153, v153, v15
	v_add_f32_e32 v154, 1.0, v154
	v_add_f32_e32 v155, 1.0, v155
	v_rcp_f32_e32 v154, v154
	v_rcp_f32_e32 v155, v155
	v_cvt_pk_bf16_f32 v153, v151, v153
	v_exp_f32_e64 v158, -v43
	v_mul_f32_e32 v151, v40, v154
	v_mul_f32_e32 v154, v41, v155
	v_exp_f32_e64 v155, -v42
	v_add_f32_e32 v158, 1.0, v158
	v_rcp_f32_e32 v158, v158
	v_mul_f32_e32 v151, v151, v8
	v_add_f32_e32 v155, 1.0, v155
	v_rcp_f32_e32 v155, v155
	v_mul_f32_e32 v154, v154, v9
	v_cvt_pk_bf16_f32 v154, v151, v154
	v_mul_f32_e32 v151, v42, v155
	v_mul_f32_e32 v155, v43, v158
	v_mul_f32_e32 v151, v151, v10
	v_mul_f32_e32 v155, v155, v11
	v_cvt_pk_bf16_f32 v155, v151, v155
	s_mul_i32 s98, s47, 160
	s_add_u32 s98, s16, s98
	s_addc_u32 s99, s17, 0
	global_store_dwordx4 v156, v[152:155], s[98:99]
	s_nop 0
	v_exp_f32_e64 v151, -v36
	v_exp_f32_e64 v152, -v37
	v_add_f32_e32 v150, 1.0, v151
	v_rcp_f32_e32 v153, v150
	v_add_f32_e32 v150, 1.0, v152
	v_rcp_f32_e32 v152, v150
	v_exp_f32_e64 v144, -v38
	v_exp_f32_e64 v145, -v39
	v_mul_f32_e32 v142, v36, v153
	v_mul_f32_e32 v143, v37, v152
	v_add_f32_e32 v144, 1.0, v144
	v_add_f32_e32 v145, 1.0, v145
	v_rcp_f32_e32 v144, v144
	v_rcp_f32_e32 v145, v145
	v_mul_f32_e32 v142, v142, v4
	v_mul_f32_e32 v143, v143, v5
	v_cvt_pk_bf16_f32 v142, v142, v143
	v_mul_f32_e32 v143, v38, v144
	v_mul_f32_e32 v144, v39, v145
	v_exp_f32_e64 v145, -v32
	v_exp_f32_e64 v152, -v33
	v_mul_f32_e32 v143, v143, v6
	v_mul_f32_e32 v144, v144, v7
	v_add_f32_e32 v145, 1.0, v145
	v_add_f32_e32 v152, 1.0, v152
	v_rcp_f32_e32 v145, v145
	v_rcp_f32_e32 v152, v152
	v_cvt_pk_bf16_f32 v143, v143, v144
	v_mul_f32_e32 v144, v32, v145
	v_mul_f32_e32 v145, v33, v152
	v_exp_f32_e64 v152, -v34
	v_exp_f32_e64 v153, -v35
	v_mul_f32_e32 v144, v144, v0
	v_mul_f32_e32 v145, v145, v1
	v_add_f32_e32 v152, 1.0, v152
	v_rcp_f32_e32 v152, v152
	v_add_f32_e32 v153, 1.0, v153
	v_rcp_f32_e32 v153, v153
	v_cvt_pk_bf16_f32 v144, v144, v145
	v_mul_f32_e32 v145, v34, v152
	v_mul_f32_e32 v145, v145, v2
	v_mul_f32_e32 v152, v35, v153
	v_mul_f32_e32 v152, v152, v3
	v_cvt_pk_bf16_f32 v145, v145, v152
	s_mul_i32 s98, s47, 176
	s_add_u32 s98, s16, s98
	s_addc_u32 s99, s17, 0
	global_store_dwordx4 v156, v[142:145], s[98:99]
	s_cbranch_vccnz .LBB0_1265
	s_andn2_b64 vcc, exec, s[10:11]
	s_cbranch_vccnz .LBB0_1264
	s_barrier
	s_branch .LBB0_1264
